# early buffer_inv: acquire invalidate issued right after the arrival atomic returns instead of after the release poll
# baseline (speedup 1.0000x reference)
.LBB0_167:
	v_readlane_b32 s0, v251, 23
	s_lshl_b32 s0, s0, 2
	s_add_u32 s21, s34, s0
	s_addc_u32 s20, s35, 0
	v_mov_b32_e32 v1, s21
	v_add_co_u32_e32 v6, vcc, 0x1000, v1
	v_mov_b32_e32 v1, s20
	s_nop 0
	v_addc_co_u32_e32 v7, vcc, 0, v1, vcc
	v_mov_b32_e32 v1, 1
	flat_atomic_add v1, v[6:7], v1 offset:1024 sc0
	v_cvt_f32_u32_e32 v3, v4
	v_sub_u32_e32 v5, 0, v4
	v_readlane_b32 s1, v251, 24
	v_rcp_iflag_f32_e32 v3, v3
	s_nop 0
	v_mul_f32_e32 v3, 0x4f7ffffe, v3
	v_cvt_u32_f32_e32 v3, v3
	v_mul_lo_u32 v5, v5, v3
	v_mul_hi_u32 v5, v3, v5
	v_add_u32_e32 v3, v3, v5
	s_waitcnt vmcnt(0) lgkmcnt(0)
	buffer_inv sc1
	v_mul_hi_u32 v3, v1, v3
	v_mul_lo_u32 v5, v3, v4
	v_add_u32_e32 v6, 1, v1
	v_sub_u32_e32 v1, v1, v5
	v_add_u32_e32 v7, 1, v3
	v_cmp_ge_u32_e32 vcc, v1, v4
	v_sub_u32_e32 v5, v1, v4
	s_nop 0
	v_cndmask_b32_e32 v3, v3, v7, vcc
	v_cndmask_b32_e32 v1, v1, v5, vcc
	v_add_u32_e32 v5, 1, v3
	v_cmp_ge_u32_e32 vcc, v1, v4
	s_nop 1
	v_cndmask_b32_e32 v1, v3, v5, vcc
	v_mad_u64_u32 v[4:5], s[0:1], v4, v1, v[4:5]
	v_cmp_ne_u32_e32 vcc, v6, v4
	s_and_saveexec_b64 s[0:1], vcc
	s_xor_b64 s[0:1], exec, s[0:1]
	s_cbranch_execz .LBB0_180
	v_mov_b32_e32 v2, s21
	v_add_co_u32_e32 v2, vcc, 0x2000, v2
	v_mov_b32_e32 v3, s20
	s_nop 0
	v_addc_co_u32_e32 v3, vcc, 0, v3, vcc
	flat_load_dword v2, v[2:3] offset:1024 sc1
	s_add_u32 s4, s21, 0x2400
	s_addc_u32 s5, s20, 0
	s_waitcnt vmcnt(0) lgkmcnt(0)
	v_cmp_eq_u32_e32 vcc, v2, v1
	s_and_saveexec_b64 s[2:3], vcc
	s_cbranch_execz .LBB0_179
	s_mov_b32 s22, 1
	s_mov_b64 s[6:7], 0
	s_branch .LBB0_171

.LBB0_179:
	s_or_b64 exec, exec, s[2:3]
	s_waitcnt vmcnt(0) lgkmcnt(0)
	s_waitcnt vmcnt(0)

.LBB0_195:
	s_or_b64 exec, exec, s[0:1]
	v_mov_b32_e32 v1, s21
	v_add_co_u32_e32 v2, vcc, 0x2000, v1
	v_mov_b32_e32 v1, s20
	s_nop 0
	v_addc_co_u32_e32 v3, vcc, 0, v1, vcc
	v_mov_b32_e32 v1, 1
	s_waitcnt vmcnt(0) lgkmcnt(0)
	flat_atomic_add v[2:3], v1 offset:1024
	s_waitcnt vmcnt(0)

.LBB0_198:
	s_or_b64 exec, exec, s[2:3]
	v_mov_b32_e32 v2, s28
	v_add_co_u32_e32 v2, vcc, 0x2000, v2
	v_mov_b32_e32 v3, s25
	s_nop 0
	v_addc_co_u32_e32 v3, vcc, 0, v3, vcc
	s_waitcnt vmcnt(0) lgkmcnt(0)
	flat_atomic_add v[2:3], v207 offset:1024
	s_waitcnt vmcnt(0)

.LBB0_247:
	v_readlane_b32 s4, v251, 23
	v_readlane_b32 s5, v251, 24
	s_lshl_b64 s[4:5], s[4:5], 2
	s_add_u32 s38, s2, s4
	s_addc_u32 s28, s3, s5
	v_mov_b32_e32 v3, s38
	v_add_co_u32_e32 v6, vcc, 0x1000, v3
	v_mov_b32_e32 v3, s28
	s_nop 0
	v_addc_co_u32_e32 v7, vcc, 0, v3, vcc
	flat_atomic_add v5, v[6:7], v207 offset:1024 sc0
	v_cvt_f32_u32_e32 v3, v4
	v_sub_u32_e32 v6, 0, v4
	v_rcp_iflag_f32_e32 v3, v3
	s_nop 0
	v_mul_f32_e32 v3, 0x4f7ffffe, v3
	v_cvt_u32_f32_e32 v3, v3
	v_mul_lo_u32 v6, v6, v3
	v_mul_hi_u32 v6, v3, v6
	v_add_u32_e32 v3, v3, v6
	s_waitcnt vmcnt(0) lgkmcnt(0)
	buffer_inv sc1
	v_mul_hi_u32 v3, v5, v3
	v_mul_lo_u32 v6, v3, v4
	v_sub_u32_e32 v6, v5, v6
	v_cmp_ge_u32_e32 vcc, v6, v4
	v_add_u32_e32 v7, 1, v3
	s_nop 0
	v_cndmask_b32_e32 v3, v3, v7, vcc
	v_sub_u32_e32 v7, v6, v4
	v_cndmask_b32_e32 v6, v6, v7, vcc
	v_cmp_ge_u32_e32 vcc, v6, v4
	v_add_u32_e32 v6, 1, v3
	s_nop 0
	v_cndmask_b32_e32 v3, v3, v6, vcc
	v_add_u32_e32 v6, 1, v5
	v_mad_u64_u32 v[4:5], s[4:5], v4, v3, v[4:5]
	v_cmp_ne_u32_e32 vcc, v6, v4
	s_and_saveexec_b64 s[4:5], vcc
	s_xor_b64 s[4:5], exec, s[4:5]
	s_cbranch_execz .LBB0_260
	v_mov_b32_e32 v2, s38
	v_add_co_u32_e32 v4, vcc, 0x2000, v2
	v_mov_b32_e32 v2, s28
	s_nop 0
	v_addc_co_u32_e32 v5, vcc, 0, v2, vcc
	flat_load_dword v2, v[4:5] offset:1024 sc1
	s_add_u32 s10, s38, 0x2400
	s_addc_u32 s11, s28, 0
	s_waitcnt vmcnt(0) lgkmcnt(0)
	v_cmp_eq_u32_e32 vcc, v2, v3
	s_and_saveexec_b64 s[8:9], vcc
	s_cbranch_execz .LBB0_259
	s_mov_b32 s39, 1
	s_mov_b64 s[12:13], 0
	s_branch .LBB0_251

.LBB0_259:
	s_or_b64 exec, exec, s[8:9]
	s_waitcnt vmcnt(0) lgkmcnt(0)
	s_waitcnt vmcnt(0)

.LBB0_275:
	s_or_b64 exec, exec, s[2:3]
	v_mov_b32_e32 v2, s38
	v_add_co_u32_e32 v2, vcc, 0x2000, v2
	v_mov_b32_e32 v3, s28
	s_nop 0
	v_addc_co_u32_e32 v3, vcc, 0, v3, vcc
	s_waitcnt vmcnt(0) lgkmcnt(0)
	flat_atomic_add v[2:3], v207 offset:1024
	s_waitcnt vmcnt(0)

.LBB0_1364:
	v_readlane_b32 s4, v251, 23
	v_readlane_b32 s5, v251, 24
	s_lshl_b64 s[4:5], s[4:5], 2
	s_add_u32 s36, s2, s4
	s_addc_u32 s28, s3, s5
	v_mov_b32_e32 v3, s36
	v_add_co_u32_e32 v6, vcc, 0x1000, v3
	v_mov_b32_e32 v3, s28
	s_nop 0
	v_addc_co_u32_e32 v7, vcc, 0, v3, vcc
	flat_atomic_add v5, v[6:7], v207 offset:1024 sc0
	v_cvt_f32_u32_e32 v3, v4
	v_sub_u32_e32 v6, 0, v4
	v_rcp_iflag_f32_e32 v3, v3
	s_nop 0
	v_mul_f32_e32 v3, 0x4f7ffffe, v3
	v_cvt_u32_f32_e32 v3, v3
	v_mul_lo_u32 v6, v6, v3
	v_mul_hi_u32 v6, v3, v6
	v_add_u32_e32 v3, v3, v6
	s_waitcnt vmcnt(0) lgkmcnt(0)
	buffer_inv sc1
	v_mul_hi_u32 v3, v5, v3
	v_mul_lo_u32 v6, v3, v4
	v_sub_u32_e32 v6, v5, v6
	v_cmp_ge_u32_e32 vcc, v6, v4
	v_add_u32_e32 v7, 1, v3
	s_nop 0
	v_cndmask_b32_e32 v3, v3, v7, vcc
	v_sub_u32_e32 v7, v6, v4
	v_cndmask_b32_e32 v6, v6, v7, vcc
	v_cmp_ge_u32_e32 vcc, v6, v4
	v_add_u32_e32 v6, 1, v3
	s_nop 0
	v_cndmask_b32_e32 v3, v3, v6, vcc
	v_add_u32_e32 v6, 1, v5
	v_mad_u64_u32 v[4:5], s[4:5], v4, v3, v[4:5]
	v_cmp_ne_u32_e32 vcc, v6, v4
	s_and_saveexec_b64 s[4:5], vcc
	s_xor_b64 s[4:5], exec, s[4:5]
	s_cbranch_execz .LBB0_1377
	v_mov_b32_e32 v2, s36
	v_add_co_u32_e32 v4, vcc, 0x2000, v2
	v_mov_b32_e32 v2, s28
	s_nop 0
	v_addc_co_u32_e32 v5, vcc, 0, v2, vcc
	flat_load_dword v2, v[4:5] offset:1024 sc1
	s_add_u32 s8, s36, 0x2400
	s_addc_u32 s9, s28, 0
	s_waitcnt vmcnt(0) lgkmcnt(0)
	v_cmp_eq_u32_e32 vcc, v2, v3
	s_and_saveexec_b64 s[6:7], vcc
	s_cbranch_execz .LBB0_1376
	s_mov_b32 s37, 1
	s_mov_b64 s[10:11], 0
	s_branch .LBB0_1368

.LBB0_1376:
	s_or_b64 exec, exec, s[6:7]
	s_waitcnt vmcnt(0) lgkmcnt(0)
	s_waitcnt vmcnt(0)

.LBB0_1392:
	s_or_b64 exec, exec, s[2:3]
	v_mov_b32_e32 v2, s36
	v_add_co_u32_e32 v2, vcc, 0x2000, v2
	v_mov_b32_e32 v3, s28
	s_nop 0
	v_addc_co_u32_e32 v3, vcc, 0, v3, vcc
	s_waitcnt vmcnt(0) lgkmcnt(0)
	flat_atomic_add v[2:3], v207 offset:1024
	s_waitcnt vmcnt(0)

.LBB0_1523:
	v_readlane_b32 s4, v251, 23
	v_readlane_b32 s5, v251, 24
	s_lshl_b64 s[4:5], s[4:5], 2
	s_add_u32 s38, s2, s4
	s_addc_u32 s28, s3, s5
	v_mov_b32_e32 v3, s38
	v_add_co_u32_e32 v6, vcc, 0x1000, v3
	v_mov_b32_e32 v3, s28
	s_nop 0
	v_addc_co_u32_e32 v7, vcc, 0, v3, vcc
	flat_atomic_add v5, v[6:7], v207 offset:1024 sc0
	v_cvt_f32_u32_e32 v3, v4
	v_sub_u32_e32 v6, 0, v4
	v_rcp_iflag_f32_e32 v3, v3
	s_nop 0
	v_mul_f32_e32 v3, 0x4f7ffffe, v3
	v_cvt_u32_f32_e32 v3, v3
	v_mul_lo_u32 v6, v6, v3
	v_mul_hi_u32 v6, v3, v6
	v_add_u32_e32 v3, v3, v6
	s_waitcnt vmcnt(0) lgkmcnt(0)
	buffer_inv sc1
	v_mul_hi_u32 v3, v5, v3
	v_mul_lo_u32 v6, v3, v4
	v_sub_u32_e32 v6, v5, v6
	v_cmp_ge_u32_e32 vcc, v6, v4
	v_add_u32_e32 v7, 1, v3
	s_nop 0
	v_cndmask_b32_e32 v3, v3, v7, vcc
	v_sub_u32_e32 v7, v6, v4
	v_cndmask_b32_e32 v6, v6, v7, vcc
	v_cmp_ge_u32_e32 vcc, v6, v4
	v_add_u32_e32 v6, 1, v3
	s_nop 0
	v_cndmask_b32_e32 v3, v3, v6, vcc
	v_add_u32_e32 v6, 1, v5
	v_mad_u64_u32 v[4:5], s[4:5], v4, v3, v[4:5]
	v_cmp_ne_u32_e32 vcc, v6, v4
	s_and_saveexec_b64 s[4:5], vcc
	s_xor_b64 s[4:5], exec, s[4:5]
	s_cbranch_execz .LBB0_1536
	v_mov_b32_e32 v2, s38
	v_add_co_u32_e32 v4, vcc, 0x2000, v2
	v_mov_b32_e32 v2, s28
	s_nop 0
	v_addc_co_u32_e32 v5, vcc, 0, v2, vcc
	flat_load_dword v2, v[4:5] offset:1024 sc1
	s_add_u32 s8, s38, 0x2400
	s_addc_u32 s9, s28, 0
	s_waitcnt vmcnt(0) lgkmcnt(0)
	v_cmp_eq_u32_e32 vcc, v2, v3
	s_and_saveexec_b64 s[6:7], vcc
	s_cbranch_execz .LBB0_1535
	s_mov_b32 s39, 1
	s_mov_b64 s[10:11], 0
	s_branch .LBB0_1527

.LBB0_1795:
	v_readlane_b32 s4, v251, 23
	v_readlane_b32 s5, v251, 24
	s_lshl_b64 s[4:5], s[4:5], 2
	s_add_u32 s28, s2, s4
	s_addc_u32 s25, s3, s5
	v_mov_b32_e32 v3, s28
	v_add_co_u32_e32 v6, vcc, 0x1000, v3
	v_mov_b32_e32 v3, s25
	s_nop 0
	v_addc_co_u32_e32 v7, vcc, 0, v3, vcc
	flat_atomic_add v5, v[6:7], v207 offset:1024 sc0
	v_cvt_f32_u32_e32 v3, v4
	v_sub_u32_e32 v6, 0, v4
	v_rcp_iflag_f32_e32 v3, v3
	s_nop 0
	v_mul_f32_e32 v3, 0x4f7ffffe, v3
	v_cvt_u32_f32_e32 v3, v3
	v_mul_lo_u32 v6, v6, v3
	v_mul_hi_u32 v6, v3, v6
	v_add_u32_e32 v3, v3, v6
	s_waitcnt vmcnt(0) lgkmcnt(0)
	buffer_inv sc1
	v_mul_hi_u32 v3, v5, v3
	v_mul_lo_u32 v6, v3, v4
	v_sub_u32_e32 v6, v5, v6
	v_cmp_ge_u32_e32 vcc, v6, v4
	v_add_u32_e32 v7, 1, v3
	s_nop 0
	v_cndmask_b32_e32 v3, v3, v7, vcc
	v_sub_u32_e32 v7, v6, v4
	v_cndmask_b32_e32 v6, v6, v7, vcc
	v_cmp_ge_u32_e32 vcc, v6, v4
	v_add_u32_e32 v6, 1, v3
	s_nop 0
	v_cndmask_b32_e32 v3, v3, v6, vcc
	v_add_u32_e32 v6, 1, v5
	v_mad_u64_u32 v[4:5], s[4:5], v4, v3, v[4:5]
	v_cmp_ne_u32_e32 vcc, v6, v4
	s_and_saveexec_b64 s[4:5], vcc
	s_xor_b64 s[4:5], exec, s[4:5]
	s_cbranch_execz .LBB0_1808
	v_mov_b32_e32 v2, s28
	v_add_co_u32_e32 v4, vcc, 0x2000, v2
	v_mov_b32_e32 v2, s25
	s_nop 0
	v_addc_co_u32_e32 v5, vcc, 0, v2, vcc
	flat_load_dword v2, v[4:5] offset:1024 sc1
	s_add_u32 s8, s28, 0x2400
	s_addc_u32 s9, s25, 0
	s_waitcnt vmcnt(0) lgkmcnt(0)
	v_cmp_eq_u32_e32 vcc, v2, v3
	s_and_saveexec_b64 s[6:7], vcc
	s_cbranch_execz .LBB0_1807
	s_mov_b32 s36, 1
	s_mov_b64 s[10:11], 0
	s_branch .LBB0_1799
